# Epi2 restructured into three straight-line bodies (no rotation / rotate bj=0 / rotate bj=1) chosen by one branch
# speedup vs baseline: 1.0059x; 1.0059x over previous
.LBB0_837:
	s_cmp_gt_i32 s54, 15
	s_cselect_b32 s2, 1, 0
	s_lshl_b32 s54, s54, 8
	s_add_i32 s54, s54, s44
	s_lshl_b32 s6, s55, 8
	s_or_b32 s60, s6, s45
	v_or_b32_e32 v216, s54, v200
	v_mul_u32_u24_e32 v217, 0x90, v216
	v_add_u32_e32 v218, 0x1200, v217
	global_load_dwordx4 v[112:115], v217, s[12:13]
	global_load_dwordx4 v[116:119], v217, s[12:13] offset:16
	global_load_dwordx4 v[120:123], v217, s[12:13] offset:32
	global_load_dwordx4 v[132:135], v217, s[12:13] offset:2304
	global_load_dwordx4 v[136:139], v217, s[12:13] offset:2320
	global_load_dwordx4 v[140:143], v217, s[12:13] offset:2336
	global_load_dwordx4 v[152:155], v218, s[12:13]
	global_load_dwordx4 v[156:159], v218, s[12:13] offset:16
	global_load_dwordx4 v[160:163], v218, s[12:13] offset:32
	global_load_dwordx4 v[184:187], v218, s[12:13] offset:2304
	global_load_dwordx4 v[188:191], v218, s[12:13] offset:2320
	global_load_dwordx4 v[192:195], v218, s[12:13] offset:2336
	s_mul_hi_i32 s6, s60, 0x2aaaaaab
	s_lshr_b32 s7, s6, 31
	s_lshr_b32 s6, s6, 4
	s_add_i32 s6, s6, s7
	s_mulk_i32 s6, 0x60
	s_sub_i32 s6, s60, s6
	s_cmp_eq_u32 s6, 64
	s_cselect_b32 s61, 1, 0
	s_and_b32 s61, s61, s2
	s_or_b32 s8, s60, 0x80
	s_mul_hi_i32 s6, s8, 0x2aaaaaab
	s_lshr_b32 s7, s6, 31
	s_lshr_b32 s6, s6, 4
	s_add_i32 s6, s6, s7
	s_mulk_i32 s6, 0x60
	s_sub_i32 s6, s8, s6
	s_cmp_eq_u32 s6, 64
	s_cselect_b32 s62, 1, 0
	s_and_b32 s62, s62, s2
	s_bfe_u32 s55, s54, 0x40006
	v_xor_b32_e32 v213, 16, v209
	v_lshlrev_b32_e32 v213, 2, v213
	v_mul_u32_u24_e32 v211, 0x600, v216
	s_lshl_b32 s6, s60, 1
	v_add3_u32 v211, v211, v172, s6
	v_add_u32_e32 v217, 0x4800, v217
	v_add_u32_e32 v218, 0x4800, v218
	s_waitcnt vmcnt(0)
	v_pk_add_f32 v[112:113], v[112:113], v[114:115]
	v_pk_add_f32 v[116:117], v[116:117], v[118:119]
	v_pk_add_f32 v[120:121], v[120:121], v[122:123]
	v_pk_add_f32 v[112:113], v[112:113], v[116:117]
	v_pk_add_f32 v[112:113], v[112:113], v[120:121]
	v_add_f32_e32 v112, v112, v113
	v_fmamk_f32 v112, v112, 0x3b2aaaab, v208
	v_pk_add_f32 v[132:133], v[132:133], v[134:135]
	v_pk_add_f32 v[136:137], v[136:137], v[138:139]
	v_pk_add_f32 v[140:141], v[140:141], v[142:143]
	v_pk_add_f32 v[132:133], v[132:133], v[136:137]
	v_pk_add_f32 v[132:133], v[132:133], v[140:141]
	v_add_f32_e32 v132, v132, v133
	v_fmamk_f32 v132, v132, 0x3b2aaaab, v208
	v_pk_add_f32 v[152:153], v[152:153], v[154:155]
	v_pk_add_f32 v[156:157], v[156:157], v[158:159]
	v_pk_add_f32 v[160:161], v[160:161], v[162:163]
	v_pk_add_f32 v[152:153], v[152:153], v[156:157]
	v_pk_add_f32 v[152:153], v[152:153], v[160:161]
	v_add_f32_e32 v152, v152, v153
	v_fmamk_f32 v152, v152, 0x3b2aaaab, v208
	v_pk_add_f32 v[184:185], v[184:185], v[186:187]
	v_pk_add_f32 v[188:189], v[188:189], v[190:191]
	v_pk_add_f32 v[192:193], v[192:193], v[194:195]
	v_pk_add_f32 v[184:185], v[184:185], v[188:189]
	v_pk_add_f32 v[184:185], v[184:185], v[192:193]
	v_add_f32_e32 v184, v184, v185
	v_fmamk_f32 v184, v184, 0x3b2aaaab, v208
	v_rsq_f32_e32 v196, v112
	v_rsq_f32_e32 v198, v132
	v_rsq_f32_e32 v210, v152
	v_rsq_f32_e32 v212, v184
	s_nop 0
	v_mul_f32_e32 v196, 0x3e16c740, v196
	v_mul_f32_e32 v198, 0x3e16c740, v198
	v_mul_f32_e32 v210, 0x3e16c740, v210
	v_mul_f32_e32 v212, 0x3e16c740, v212
	global_load_dwordx4 v[112:115], v217, s[12:13]
	global_load_dwordx4 v[116:119], v217, s[12:13] offset:16
	global_load_dwordx4 v[120:123], v217, s[12:13] offset:32
	global_load_dwordx4 v[132:135], v217, s[12:13] offset:2304
	global_load_dwordx4 v[136:139], v217, s[12:13] offset:2320
	global_load_dwordx4 v[140:143], v217, s[12:13] offset:2336
	global_load_dwordx4 v[152:155], v218, s[12:13]
	global_load_dwordx4 v[156:159], v218, s[12:13] offset:16
	global_load_dwordx4 v[160:163], v218, s[12:13] offset:32
	global_load_dwordx4 v[184:187], v218, s[12:13] offset:2304
	global_load_dwordx4 v[188:191], v218, s[12:13] offset:2320
	global_load_dwordx4 v[192:195], v218, s[12:13] offset:2336
	s_add_i32 s6, s54, 0x80
	s_bfe_u32 s7, s6, 0x40006
	s_cmp_lg_u32 s61, 0
	s_cbranch_scc1 .Lq2_v0
	s_cmp_lg_u32 s62, 0
	s_cbranch_scc1 .Lq2_v1
	v_pk_mul_f32 v[148:149], v[148:149], v[196:197] op_sel_hi:[1,0]
	v_pk_mul_f32 v[150:151], v[150:151], v[196:197] op_sel_hi:[1,0]
	v_pk_mul_f32 v[144:145], v[144:145], v[196:197] op_sel_hi:[1,0]
	v_pk_mul_f32 v[146:147], v[146:147], v[196:197] op_sel_hi:[1,0]
	v_cvt_pk_bf16_f32 v148, v148, v149
	v_cvt_pk_bf16_f32 v149, v150, v151
	v_cvt_pk_bf16_f32 v150, v144, v145
	v_cvt_pk_bf16_f32 v151, v146, v147
	global_store_dwordx4 v211, v[148:151], s[16:17]
	v_pk_mul_f32 v[128:129], v[128:129], v[196:197] op_sel_hi:[1,0]
	v_pk_mul_f32 v[130:131], v[130:131], v[196:197] op_sel_hi:[1,0]
	v_pk_mul_f32 v[124:125], v[124:125], v[196:197] op_sel_hi:[1,0]
	v_pk_mul_f32 v[126:127], v[126:127], v[196:197] op_sel_hi:[1,0]
	v_cvt_pk_bf16_f32 v128, v128, v129
	v_cvt_pk_bf16_f32 v129, v130, v131
	v_cvt_pk_bf16_f32 v130, v124, v125
	v_cvt_pk_bf16_f32 v131, v126, v127
	global_store_dwordx4 v211, v[128:131], s[16:17] offset:256
	v_add_u32_e32 v197, 0x6000, v211
	v_pk_mul_f32 v[108:109], v[108:109], v[198:199] op_sel_hi:[1,0]
	v_pk_mul_f32 v[110:111], v[110:111], v[198:199] op_sel_hi:[1,0]
	v_pk_mul_f32 v[104:105], v[104:105], v[198:199] op_sel_hi:[1,0]
	v_pk_mul_f32 v[106:107], v[106:107], v[198:199] op_sel_hi:[1,0]
	v_cvt_pk_bf16_f32 v108, v108, v109
	v_cvt_pk_bf16_f32 v109, v110, v111
	v_cvt_pk_bf16_f32 v110, v104, v105
	v_cvt_pk_bf16_f32 v111, v106, v107
	global_store_dwordx4 v197, v[108:111], s[16:17]
	v_pk_mul_f32 v[100:101], v[100:101], v[198:199] op_sel_hi:[1,0]
	v_pk_mul_f32 v[102:103], v[102:103], v[198:199] op_sel_hi:[1,0]
	v_pk_mul_f32 v[96:97], v[96:97], v[198:199] op_sel_hi:[1,0]
	v_pk_mul_f32 v[98:99], v[98:99], v[198:199] op_sel_hi:[1,0]
	v_cvt_pk_bf16_f32 v100, v100, v101
	v_cvt_pk_bf16_f32 v101, v102, v103
	v_cvt_pk_bf16_f32 v102, v96, v97
	v_cvt_pk_bf16_f32 v103, v98, v99
	global_store_dwordx4 v197, v[100:103], s[16:17] offset:256
	v_add_u32_e32 v197, 0xc000, v211
	v_pk_mul_f32 v[92:93], v[92:93], v[210:211] op_sel_hi:[1,0]
	v_pk_mul_f32 v[94:95], v[94:95], v[210:211] op_sel_hi:[1,0]
	v_pk_mul_f32 v[88:89], v[88:89], v[210:211] op_sel_hi:[1,0]
	v_pk_mul_f32 v[90:91], v[90:91], v[210:211] op_sel_hi:[1,0]
	v_cvt_pk_bf16_f32 v92, v92, v93
	v_cvt_pk_bf16_f32 v93, v94, v95
	v_cvt_pk_bf16_f32 v94, v88, v89
	v_cvt_pk_bf16_f32 v95, v90, v91
	global_store_dwordx4 v197, v[92:95], s[16:17]
	v_pk_mul_f32 v[84:85], v[84:85], v[210:211] op_sel_hi:[1,0]
	v_pk_mul_f32 v[86:87], v[86:87], v[210:211] op_sel_hi:[1,0]
	v_pk_mul_f32 v[80:81], v[80:81], v[210:211] op_sel_hi:[1,0]
	v_pk_mul_f32 v[82:83], v[82:83], v[210:211] op_sel_hi:[1,0]
	v_cvt_pk_bf16_f32 v84, v84, v85
	v_cvt_pk_bf16_f32 v85, v86, v87
	v_cvt_pk_bf16_f32 v86, v80, v81
	v_cvt_pk_bf16_f32 v87, v82, v83
	global_store_dwordx4 v197, v[84:87], s[16:17] offset:256
	v_add_u32_e32 v197, 0x12000, v211
	v_pk_mul_f32 v[76:77], v[76:77], v[212:213] op_sel_hi:[1,0]
	v_pk_mul_f32 v[78:79], v[78:79], v[212:213] op_sel_hi:[1,0]
	v_pk_mul_f32 v[72:73], v[72:73], v[212:213] op_sel_hi:[1,0]
	v_pk_mul_f32 v[74:75], v[74:75], v[212:213] op_sel_hi:[1,0]
	v_cvt_pk_bf16_f32 v76, v76, v77
	v_cvt_pk_bf16_f32 v77, v78, v79
	v_cvt_pk_bf16_f32 v78, v72, v73
	v_cvt_pk_bf16_f32 v79, v74, v75
	global_store_dwordx4 v197, v[76:79], s[16:17]
	v_pk_mul_f32 v[68:69], v[68:69], v[212:213] op_sel_hi:[1,0]
	v_pk_mul_f32 v[70:71], v[70:71], v[212:213] op_sel_hi:[1,0]
	v_pk_mul_f32 v[64:65], v[64:65], v[212:213] op_sel_hi:[1,0]
	v_pk_mul_f32 v[66:67], v[66:67], v[212:213] op_sel_hi:[1,0]
	v_cvt_pk_bf16_f32 v68, v68, v69
	v_cvt_pk_bf16_f32 v69, v70, v71
	v_cvt_pk_bf16_f32 v70, v64, v65
	v_cvt_pk_bf16_f32 v71, v66, v67
	global_store_dwordx4 v197, v[68:71], s[16:17] offset:256
	s_waitcnt vmcnt(8)
	v_pk_add_f32 v[112:113], v[112:113], v[114:115]
	v_pk_add_f32 v[116:117], v[116:117], v[118:119]
	v_pk_add_f32 v[120:121], v[120:121], v[122:123]
	v_pk_add_f32 v[112:113], v[112:113], v[116:117]
	v_pk_add_f32 v[112:113], v[112:113], v[120:121]
	v_add_f32_e32 v112, v112, v113
	v_fmamk_f32 v112, v112, 0x3b2aaaab, v208
	v_pk_add_f32 v[132:133], v[132:133], v[134:135]
	v_pk_add_f32 v[136:137], v[136:137], v[138:139]
	v_pk_add_f32 v[140:141], v[140:141], v[142:143]
	v_pk_add_f32 v[132:133], v[132:133], v[136:137]
	v_pk_add_f32 v[132:133], v[132:133], v[140:141]
	v_add_f32_e32 v132, v132, v133
	v_fmamk_f32 v132, v132, 0x3b2aaaab, v208
	v_pk_add_f32 v[152:153], v[152:153], v[154:155]
	v_pk_add_f32 v[156:157], v[156:157], v[158:159]
	v_pk_add_f32 v[160:161], v[160:161], v[162:163]
	v_pk_add_f32 v[152:153], v[152:153], v[156:157]
	v_pk_add_f32 v[152:153], v[152:153], v[160:161]
	v_add_f32_e32 v152, v152, v153
	v_fmamk_f32 v152, v152, 0x3b2aaaab, v208
	v_pk_add_f32 v[184:185], v[184:185], v[186:187]
	v_pk_add_f32 v[188:189], v[188:189], v[190:191]
	v_pk_add_f32 v[192:193], v[192:193], v[194:195]
	v_pk_add_f32 v[184:185], v[184:185], v[188:189]
	v_pk_add_f32 v[184:185], v[184:185], v[192:193]
	v_add_f32_e32 v184, v184, v185
	v_fmamk_f32 v184, v184, 0x3b2aaaab, v208
	v_rsq_f32_e32 v196, v112
	v_rsq_f32_e32 v198, v132
	v_rsq_f32_e32 v210, v152
	v_rsq_f32_e32 v212, v184
	s_nop 0
	v_mul_f32_e32 v196, 0x3e16c740, v196
	v_mul_f32_e32 v198, 0x3e16c740, v198
	v_mul_f32_e32 v210, 0x3e16c740, v210
	v_mul_f32_e32 v212, 0x3e16c740, v212
	v_add_u32_e32 v197, 0x30000, v211
	v_pk_mul_f32 v[60:61], v[60:61], v[196:197] op_sel_hi:[1,0]
	v_pk_mul_f32 v[62:63], v[62:63], v[196:197] op_sel_hi:[1,0]
	v_pk_mul_f32 v[56:57], v[56:57], v[196:197] op_sel_hi:[1,0]
	v_pk_mul_f32 v[58:59], v[58:59], v[196:197] op_sel_hi:[1,0]
	v_cvt_pk_bf16_f32 v60, v60, v61
	v_cvt_pk_bf16_f32 v61, v62, v63
	v_cvt_pk_bf16_f32 v62, v56, v57
	v_cvt_pk_bf16_f32 v63, v58, v59
	global_store_dwordx4 v197, v[60:63], s[16:17]
	v_pk_mul_f32 v[52:53], v[52:53], v[196:197] op_sel_hi:[1,0]
	v_pk_mul_f32 v[54:55], v[54:55], v[196:197] op_sel_hi:[1,0]
	v_pk_mul_f32 v[48:49], v[48:49], v[196:197] op_sel_hi:[1,0]
	v_pk_mul_f32 v[50:51], v[50:51], v[196:197] op_sel_hi:[1,0]
	v_cvt_pk_bf16_f32 v52, v52, v53
	v_cvt_pk_bf16_f32 v53, v54, v55
	v_cvt_pk_bf16_f32 v54, v48, v49
	v_cvt_pk_bf16_f32 v55, v50, v51
	global_store_dwordx4 v197, v[52:55], s[16:17] offset:256
	v_add_u32_e32 v197, 0x36000, v211
	v_pk_mul_f32 v[44:45], v[44:45], v[198:199] op_sel_hi:[1,0]
	v_pk_mul_f32 v[46:47], v[46:47], v[198:199] op_sel_hi:[1,0]
	v_pk_mul_f32 v[40:41], v[40:41], v[198:199] op_sel_hi:[1,0]
	v_pk_mul_f32 v[42:43], v[42:43], v[198:199] op_sel_hi:[1,0]
	v_cvt_pk_bf16_f32 v44, v44, v45
	v_cvt_pk_bf16_f32 v45, v46, v47
	v_cvt_pk_bf16_f32 v46, v40, v41
	v_cvt_pk_bf16_f32 v47, v42, v43
	global_store_dwordx4 v197, v[44:47], s[16:17]
	v_pk_mul_f32 v[36:37], v[36:37], v[198:199] op_sel_hi:[1,0]
	v_pk_mul_f32 v[38:39], v[38:39], v[198:199] op_sel_hi:[1,0]
	v_pk_mul_f32 v[32:33], v[32:33], v[198:199] op_sel_hi:[1,0]
	v_pk_mul_f32 v[34:35], v[34:35], v[198:199] op_sel_hi:[1,0]
	v_cvt_pk_bf16_f32 v36, v36, v37
	v_cvt_pk_bf16_f32 v37, v38, v39
	v_cvt_pk_bf16_f32 v38, v32, v33
	v_cvt_pk_bf16_f32 v39, v34, v35
	global_store_dwordx4 v197, v[36:39], s[16:17] offset:256
	v_add_u32_e32 v197, 0x3c000, v211
	v_pk_mul_f32 v[28:29], v[28:29], v[210:211] op_sel_hi:[1,0]
	v_pk_mul_f32 v[30:31], v[30:31], v[210:211] op_sel_hi:[1,0]
	v_pk_mul_f32 v[24:25], v[24:25], v[210:211] op_sel_hi:[1,0]
	v_pk_mul_f32 v[26:27], v[26:27], v[210:211] op_sel_hi:[1,0]
	v_cvt_pk_bf16_f32 v28, v28, v29
	v_cvt_pk_bf16_f32 v29, v30, v31
	v_cvt_pk_bf16_f32 v30, v24, v25
	v_cvt_pk_bf16_f32 v31, v26, v27
	global_store_dwordx4 v197, v[28:31], s[16:17]
	v_pk_mul_f32 v[20:21], v[20:21], v[210:211] op_sel_hi:[1,0]
	v_pk_mul_f32 v[22:23], v[22:23], v[210:211] op_sel_hi:[1,0]
	v_pk_mul_f32 v[16:17], v[16:17], v[210:211] op_sel_hi:[1,0]
	v_pk_mul_f32 v[18:19], v[18:19], v[210:211] op_sel_hi:[1,0]
	v_cvt_pk_bf16_f32 v20, v20, v21
	v_cvt_pk_bf16_f32 v21, v22, v23
	v_cvt_pk_bf16_f32 v22, v16, v17
	v_cvt_pk_bf16_f32 v23, v18, v19
	global_store_dwordx4 v197, v[20:23], s[16:17] offset:256
	v_add_u32_e32 v197, 0x42000, v211
	v_pk_mul_f32 v[12:13], v[12:13], v[212:213] op_sel_hi:[1,0]
	v_pk_mul_f32 v[14:15], v[14:15], v[212:213] op_sel_hi:[1,0]
	v_pk_mul_f32 v[8:9], v[8:9], v[212:213] op_sel_hi:[1,0]
	v_pk_mul_f32 v[10:11], v[10:11], v[212:213] op_sel_hi:[1,0]
	v_cvt_pk_bf16_f32 v12, v12, v13
	v_cvt_pk_bf16_f32 v13, v14, v15
	v_cvt_pk_bf16_f32 v14, v8, v9
	v_cvt_pk_bf16_f32 v15, v10, v11
	global_store_dwordx4 v197, v[12:15], s[16:17]
	v_pk_mul_f32 v[4:5], v[4:5], v[212:213] op_sel_hi:[1,0]
	v_pk_mul_f32 v[6:7], v[6:7], v[212:213] op_sel_hi:[1,0]
	v_pk_mul_f32 v[0:1], v[0:1], v[212:213] op_sel_hi:[1,0]
	v_pk_mul_f32 v[2:3], v[2:3], v[212:213] op_sel_hi:[1,0]
	v_cvt_pk_bf16_f32 v4, v4, v5
	v_cvt_pk_bf16_f32 v5, v6, v7
	v_cvt_pk_bf16_f32 v6, v0, v1
	v_cvt_pk_bf16_f32 v7, v2, v3
	global_store_dwordx4 v197, v[4:7], s[16:17] offset:256
	s_branch .Lq2_end
.Lq2_v0:
	v_pk_mul_f32 v[148:149], v[148:149], v[196:197] op_sel_hi:[1,0]
	v_pk_mul_f32 v[150:151], v[150:151], v[196:197] op_sel_hi:[1,0]
	v_pk_mul_f32 v[144:145], v[144:145], v[196:197] op_sel_hi:[1,0]
	v_pk_mul_f32 v[146:147], v[146:147], v[196:197] op_sel_hi:[1,0]
	v_mov_b32_e32 v199, s55
	v_cndmask_b32_e64 v199, v200, v199, s[10:11]
	v_cvt_f32_ubyte0_e32 v199, v199
	v_mul_f32_e32 v199, v174, v199
	ds_bpermute_b32 v216, v213, v148
	ds_bpermute_b32 v217, v213, v149
	ds_bpermute_b32 v218, v213, v150
	ds_bpermute_b32 v219, v213, v151
	v_mul_f32_e32 v220, 0x3e22f983, v199
	v_mul_f32_e32 v221, 0x3d4e2601, v199
	v_mul_f32_e32 v222, 0x3c826136, v199
	v_mul_f32_e32 v223, 0x3ba4eb34, v199
	v_cos_f32_e32 v224, v220
	v_cos_f32_e32 v225, v221
	v_cos_f32_e32 v226, v222
	v_cos_f32_e32 v227, v223
	v_sin_f32_e32 v220, v220
	v_sin_f32_e32 v221, v221
	v_sin_f32_e32 v222, v222
	v_sin_f32_e32 v223, v223
	s_waitcnt lgkmcnt(0)
	v_pk_mul_f32 v[216:217], v[216:217], v[220:221]
	v_pk_mul_f32 v[218:219], v[218:219], v[222:223]
	v_pk_fma_f32 v[148:149], v[148:149], v[224:225], v[216:217]
	v_pk_fma_f32 v[150:151], v[150:151], v[226:227], v[218:219]
	ds_bpermute_b32 v216, v213, v144
	ds_bpermute_b32 v217, v213, v145
	ds_bpermute_b32 v218, v213, v146
	ds_bpermute_b32 v219, v213, v147
	v_mul_f32_e32 v220, 0x3ad09b8a, v199
	v_mul_f32_e32 v221, 0x3a03ef5d, v199
	v_mul_f32_e32 v222, 0x3926e2d4, v199
	v_mul_f32_e32 v223, 0x38531894, v199
	v_cos_f32_e32 v224, v220
	v_cos_f32_e32 v225, v221
	v_cos_f32_e32 v226, v222
	v_cos_f32_e32 v227, v223
	v_sin_f32_e32 v220, v220
	v_sin_f32_e32 v221, v221
	v_sin_f32_e32 v222, v222
	v_sin_f32_e32 v223, v223
	s_waitcnt lgkmcnt(0)
	v_pk_mul_f32 v[216:217], v[216:217], v[220:221]
	v_pk_mul_f32 v[218:219], v[218:219], v[222:223]
	v_pk_fma_f32 v[144:145], v[144:145], v[224:225], v[216:217]
	v_pk_fma_f32 v[146:147], v[146:147], v[226:227], v[218:219]
	v_cvt_pk_bf16_f32 v148, v148, v149
	v_cvt_pk_bf16_f32 v149, v150, v151
	v_cvt_pk_bf16_f32 v150, v144, v145
	v_cvt_pk_bf16_f32 v151, v146, v147
	global_store_dwordx4 v211, v[148:151], s[16:17]
	v_pk_mul_f32 v[128:129], v[128:129], v[196:197] op_sel_hi:[1,0]
	v_pk_mul_f32 v[130:131], v[130:131], v[196:197] op_sel_hi:[1,0]
	v_pk_mul_f32 v[124:125], v[124:125], v[196:197] op_sel_hi:[1,0]
	v_pk_mul_f32 v[126:127], v[126:127], v[196:197] op_sel_hi:[1,0]
	v_cvt_pk_bf16_f32 v128, v128, v129
	v_cvt_pk_bf16_f32 v129, v130, v131
	v_cvt_pk_bf16_f32 v130, v124, v125
	v_cvt_pk_bf16_f32 v131, v126, v127
	global_store_dwordx4 v211, v[128:131], s[16:17] offset:256
	v_add_u32_e32 v197, 0x6000, v211
	v_pk_mul_f32 v[108:109], v[108:109], v[198:199] op_sel_hi:[1,0]
	v_pk_mul_f32 v[110:111], v[110:111], v[198:199] op_sel_hi:[1,0]
	v_pk_mul_f32 v[104:105], v[104:105], v[198:199] op_sel_hi:[1,0]
	v_pk_mul_f32 v[106:107], v[106:107], v[198:199] op_sel_hi:[1,0]
	v_mov_b32_e32 v199, s55
	v_cndmask_b32_e64 v199, v202, v199, s[10:11]
	v_cvt_f32_ubyte0_e32 v199, v199
	v_mul_f32_e32 v199, v174, v199
	ds_bpermute_b32 v216, v213, v108
	ds_bpermute_b32 v217, v213, v109
	ds_bpermute_b32 v218, v213, v110
	ds_bpermute_b32 v219, v213, v111
	v_mul_f32_e32 v220, 0x3e22f983, v199
	v_mul_f32_e32 v221, 0x3d4e2601, v199
	v_mul_f32_e32 v222, 0x3c826136, v199
	v_mul_f32_e32 v223, 0x3ba4eb34, v199
	v_cos_f32_e32 v224, v220
	v_cos_f32_e32 v225, v221
	v_cos_f32_e32 v226, v222
	v_cos_f32_e32 v227, v223
	v_sin_f32_e32 v220, v220
	v_sin_f32_e32 v221, v221
	v_sin_f32_e32 v222, v222
	v_sin_f32_e32 v223, v223
	s_waitcnt lgkmcnt(0)
	v_pk_mul_f32 v[216:217], v[216:217], v[220:221]
	v_pk_mul_f32 v[218:219], v[218:219], v[222:223]
	v_pk_fma_f32 v[108:109], v[108:109], v[224:225], v[216:217]
	v_pk_fma_f32 v[110:111], v[110:111], v[226:227], v[218:219]
	ds_bpermute_b32 v216, v213, v104
	ds_bpermute_b32 v217, v213, v105
	ds_bpermute_b32 v218, v213, v106
	ds_bpermute_b32 v219, v213, v107
	v_mul_f32_e32 v220, 0x3ad09b8a, v199
	v_mul_f32_e32 v221, 0x3a03ef5d, v199
	v_mul_f32_e32 v222, 0x3926e2d4, v199
	v_mul_f32_e32 v223, 0x38531894, v199
	v_cos_f32_e32 v224, v220
	v_cos_f32_e32 v225, v221
	v_cos_f32_e32 v226, v222
	v_cos_f32_e32 v227, v223
	v_sin_f32_e32 v220, v220
	v_sin_f32_e32 v221, v221
	v_sin_f32_e32 v222, v222
	v_sin_f32_e32 v223, v223
	s_waitcnt lgkmcnt(0)
	v_pk_mul_f32 v[216:217], v[216:217], v[220:221]
	v_pk_mul_f32 v[218:219], v[218:219], v[222:223]
	v_pk_fma_f32 v[104:105], v[104:105], v[224:225], v[216:217]
	v_pk_fma_f32 v[106:107], v[106:107], v[226:227], v[218:219]
	v_cvt_pk_bf16_f32 v108, v108, v109
	v_cvt_pk_bf16_f32 v109, v110, v111
	v_cvt_pk_bf16_f32 v110, v104, v105
	v_cvt_pk_bf16_f32 v111, v106, v107
	global_store_dwordx4 v197, v[108:111], s[16:17]
	v_pk_mul_f32 v[100:101], v[100:101], v[198:199] op_sel_hi:[1,0]
	v_pk_mul_f32 v[102:103], v[102:103], v[198:199] op_sel_hi:[1,0]
	v_pk_mul_f32 v[96:97], v[96:97], v[198:199] op_sel_hi:[1,0]
	v_pk_mul_f32 v[98:99], v[98:99], v[198:199] op_sel_hi:[1,0]
	v_cvt_pk_bf16_f32 v100, v100, v101
	v_cvt_pk_bf16_f32 v101, v102, v103
	v_cvt_pk_bf16_f32 v102, v96, v97
	v_cvt_pk_bf16_f32 v103, v98, v99
	global_store_dwordx4 v197, v[100:103], s[16:17] offset:256
	v_add_u32_e32 v197, 0xc000, v211
	v_pk_mul_f32 v[92:93], v[92:93], v[210:211] op_sel_hi:[1,0]
	v_pk_mul_f32 v[94:95], v[94:95], v[210:211] op_sel_hi:[1,0]
	v_pk_mul_f32 v[88:89], v[88:89], v[210:211] op_sel_hi:[1,0]
	v_pk_mul_f32 v[90:91], v[90:91], v[210:211] op_sel_hi:[1,0]
	v_mov_b32_e32 v199, s55
	v_cndmask_b32_e64 v199, v203, v199, s[10:11]
	v_cvt_f32_ubyte0_e32 v199, v199
	v_mul_f32_e32 v199, v174, v199
	ds_bpermute_b32 v216, v213, v92
	ds_bpermute_b32 v217, v213, v93
	ds_bpermute_b32 v218, v213, v94
	ds_bpermute_b32 v219, v213, v95
	v_mul_f32_e32 v220, 0x3e22f983, v199
	v_mul_f32_e32 v221, 0x3d4e2601, v199
	v_mul_f32_e32 v222, 0x3c826136, v199
	v_mul_f32_e32 v223, 0x3ba4eb34, v199
	v_cos_f32_e32 v224, v220
	v_cos_f32_e32 v225, v221
	v_cos_f32_e32 v226, v222
	v_cos_f32_e32 v227, v223
	v_sin_f32_e32 v220, v220
	v_sin_f32_e32 v221, v221
	v_sin_f32_e32 v222, v222
	v_sin_f32_e32 v223, v223
	s_waitcnt lgkmcnt(0)
	v_pk_mul_f32 v[216:217], v[216:217], v[220:221]
	v_pk_mul_f32 v[218:219], v[218:219], v[222:223]
	v_pk_fma_f32 v[92:93], v[92:93], v[224:225], v[216:217]
	v_pk_fma_f32 v[94:95], v[94:95], v[226:227], v[218:219]
	ds_bpermute_b32 v216, v213, v88
	ds_bpermute_b32 v217, v213, v89
	ds_bpermute_b32 v218, v213, v90
	ds_bpermute_b32 v219, v213, v91
	v_mul_f32_e32 v220, 0x3ad09b8a, v199
	v_mul_f32_e32 v221, 0x3a03ef5d, v199
	v_mul_f32_e32 v222, 0x3926e2d4, v199
	v_mul_f32_e32 v223, 0x38531894, v199
	v_cos_f32_e32 v224, v220
	v_cos_f32_e32 v225, v221
	v_cos_f32_e32 v226, v222
	v_cos_f32_e32 v227, v223
	v_sin_f32_e32 v220, v220
	v_sin_f32_e32 v221, v221
	v_sin_f32_e32 v222, v222
	v_sin_f32_e32 v223, v223
	s_waitcnt lgkmcnt(0)
	v_pk_mul_f32 v[216:217], v[216:217], v[220:221]
	v_pk_mul_f32 v[218:219], v[218:219], v[222:223]
	v_pk_fma_f32 v[88:89], v[88:89], v[224:225], v[216:217]
	v_pk_fma_f32 v[90:91], v[90:91], v[226:227], v[218:219]
	v_cvt_pk_bf16_f32 v92, v92, v93
	v_cvt_pk_bf16_f32 v93, v94, v95
	v_cvt_pk_bf16_f32 v94, v88, v89
	v_cvt_pk_bf16_f32 v95, v90, v91
	global_store_dwordx4 v197, v[92:95], s[16:17]
	v_pk_mul_f32 v[84:85], v[84:85], v[210:211] op_sel_hi:[1,0]
	v_pk_mul_f32 v[86:87], v[86:87], v[210:211] op_sel_hi:[1,0]
	v_pk_mul_f32 v[80:81], v[80:81], v[210:211] op_sel_hi:[1,0]
	v_pk_mul_f32 v[82:83], v[82:83], v[210:211] op_sel_hi:[1,0]
	v_cvt_pk_bf16_f32 v84, v84, v85
	v_cvt_pk_bf16_f32 v85, v86, v87
	v_cvt_pk_bf16_f32 v86, v80, v81
	v_cvt_pk_bf16_f32 v87, v82, v83
	global_store_dwordx4 v197, v[84:87], s[16:17] offset:256
	v_add_u32_e32 v197, 0x12000, v211
	v_pk_mul_f32 v[76:77], v[76:77], v[212:213] op_sel_hi:[1,0]
	v_pk_mul_f32 v[78:79], v[78:79], v[212:213] op_sel_hi:[1,0]
	v_pk_mul_f32 v[72:73], v[72:73], v[212:213] op_sel_hi:[1,0]
	v_pk_mul_f32 v[74:75], v[74:75], v[212:213] op_sel_hi:[1,0]
	v_mov_b32_e32 v199, s55
	v_cndmask_b32_e64 v199, v204, v199, s[10:11]
	v_cvt_f32_ubyte0_e32 v199, v199
	v_mul_f32_e32 v199, v174, v199
	ds_bpermute_b32 v216, v213, v76
	ds_bpermute_b32 v217, v213, v77
	ds_bpermute_b32 v218, v213, v78
	ds_bpermute_b32 v219, v213, v79
	v_mul_f32_e32 v220, 0x3e22f983, v199
	v_mul_f32_e32 v221, 0x3d4e2601, v199
	v_mul_f32_e32 v222, 0x3c826136, v199
	v_mul_f32_e32 v223, 0x3ba4eb34, v199
	v_cos_f32_e32 v224, v220
	v_cos_f32_e32 v225, v221
	v_cos_f32_e32 v226, v222
	v_cos_f32_e32 v227, v223
	v_sin_f32_e32 v220, v220
	v_sin_f32_e32 v221, v221
	v_sin_f32_e32 v222, v222
	v_sin_f32_e32 v223, v223
	s_waitcnt lgkmcnt(0)
	v_pk_mul_f32 v[216:217], v[216:217], v[220:221]
	v_pk_mul_f32 v[218:219], v[218:219], v[222:223]
	v_pk_fma_f32 v[76:77], v[76:77], v[224:225], v[216:217]
	v_pk_fma_f32 v[78:79], v[78:79], v[226:227], v[218:219]
	ds_bpermute_b32 v216, v213, v72
	ds_bpermute_b32 v217, v213, v73
	ds_bpermute_b32 v218, v213, v74
	ds_bpermute_b32 v219, v213, v75
	v_mul_f32_e32 v220, 0x3ad09b8a, v199
	v_mul_f32_e32 v221, 0x3a03ef5d, v199
	v_mul_f32_e32 v222, 0x3926e2d4, v199
	v_mul_f32_e32 v223, 0x38531894, v199
	v_cos_f32_e32 v224, v220
	v_cos_f32_e32 v225, v221
	v_cos_f32_e32 v226, v222
	v_cos_f32_e32 v227, v223
	v_sin_f32_e32 v220, v220
	v_sin_f32_e32 v221, v221
	v_sin_f32_e32 v222, v222
	v_sin_f32_e32 v223, v223
	s_waitcnt lgkmcnt(0)
	v_pk_mul_f32 v[216:217], v[216:217], v[220:221]
	v_pk_mul_f32 v[218:219], v[218:219], v[222:223]
	v_pk_fma_f32 v[72:73], v[72:73], v[224:225], v[216:217]
	v_pk_fma_f32 v[74:75], v[74:75], v[226:227], v[218:219]
	v_cvt_pk_bf16_f32 v76, v76, v77
	v_cvt_pk_bf16_f32 v77, v78, v79
	v_cvt_pk_bf16_f32 v78, v72, v73
	v_cvt_pk_bf16_f32 v79, v74, v75
	global_store_dwordx4 v197, v[76:79], s[16:17]
	v_pk_mul_f32 v[68:69], v[68:69], v[212:213] op_sel_hi:[1,0]
	v_pk_mul_f32 v[70:71], v[70:71], v[212:213] op_sel_hi:[1,0]
	v_pk_mul_f32 v[64:65], v[64:65], v[212:213] op_sel_hi:[1,0]
	v_pk_mul_f32 v[66:67], v[66:67], v[212:213] op_sel_hi:[1,0]
	v_cvt_pk_bf16_f32 v68, v68, v69
	v_cvt_pk_bf16_f32 v69, v70, v71
	v_cvt_pk_bf16_f32 v70, v64, v65
	v_cvt_pk_bf16_f32 v71, v66, v67
	global_store_dwordx4 v197, v[68:71], s[16:17] offset:256
	s_mov_b32 s55, s7
	s_waitcnt vmcnt(8)
	v_pk_add_f32 v[112:113], v[112:113], v[114:115]
	v_pk_add_f32 v[116:117], v[116:117], v[118:119]
	v_pk_add_f32 v[120:121], v[120:121], v[122:123]
	v_pk_add_f32 v[112:113], v[112:113], v[116:117]
	v_pk_add_f32 v[112:113], v[112:113], v[120:121]
	v_add_f32_e32 v112, v112, v113
	v_fmamk_f32 v112, v112, 0x3b2aaaab, v208
	v_pk_add_f32 v[132:133], v[132:133], v[134:135]
	v_pk_add_f32 v[136:137], v[136:137], v[138:139]
	v_pk_add_f32 v[140:141], v[140:141], v[142:143]
	v_pk_add_f32 v[132:133], v[132:133], v[136:137]
	v_pk_add_f32 v[132:133], v[132:133], v[140:141]
	v_add_f32_e32 v132, v132, v133
	v_fmamk_f32 v132, v132, 0x3b2aaaab, v208
	v_pk_add_f32 v[152:153], v[152:153], v[154:155]
	v_pk_add_f32 v[156:157], v[156:157], v[158:159]
	v_pk_add_f32 v[160:161], v[160:161], v[162:163]
	v_pk_add_f32 v[152:153], v[152:153], v[156:157]
	v_pk_add_f32 v[152:153], v[152:153], v[160:161]
	v_add_f32_e32 v152, v152, v153
	v_fmamk_f32 v152, v152, 0x3b2aaaab, v208
	v_pk_add_f32 v[184:185], v[184:185], v[186:187]
	v_pk_add_f32 v[188:189], v[188:189], v[190:191]
	v_pk_add_f32 v[192:193], v[192:193], v[194:195]
	v_pk_add_f32 v[184:185], v[184:185], v[188:189]
	v_pk_add_f32 v[184:185], v[184:185], v[192:193]
	v_add_f32_e32 v184, v184, v185
	v_fmamk_f32 v184, v184, 0x3b2aaaab, v208
	v_rsq_f32_e32 v196, v112
	v_rsq_f32_e32 v198, v132
	v_rsq_f32_e32 v210, v152
	v_rsq_f32_e32 v212, v184
	s_nop 0
	v_mul_f32_e32 v196, 0x3e16c740, v196
	v_mul_f32_e32 v198, 0x3e16c740, v198
	v_mul_f32_e32 v210, 0x3e16c740, v210
	v_mul_f32_e32 v212, 0x3e16c740, v212
	v_add_u32_e32 v197, 0x30000, v211
	v_pk_mul_f32 v[60:61], v[60:61], v[196:197] op_sel_hi:[1,0]
	v_pk_mul_f32 v[62:63], v[62:63], v[196:197] op_sel_hi:[1,0]
	v_pk_mul_f32 v[56:57], v[56:57], v[196:197] op_sel_hi:[1,0]
	v_pk_mul_f32 v[58:59], v[58:59], v[196:197] op_sel_hi:[1,0]
	v_mov_b32_e32 v199, s55
	v_cndmask_b32_e64 v199, v200, v199, s[10:11]
	v_cvt_f32_ubyte0_e32 v199, v199
	v_mul_f32_e32 v199, v174, v199
	ds_bpermute_b32 v216, v213, v60
	ds_bpermute_b32 v217, v213, v61
	ds_bpermute_b32 v218, v213, v62
	ds_bpermute_b32 v219, v213, v63
	v_mul_f32_e32 v220, 0x3e22f983, v199
	v_mul_f32_e32 v221, 0x3d4e2601, v199
	v_mul_f32_e32 v222, 0x3c826136, v199
	v_mul_f32_e32 v223, 0x3ba4eb34, v199
	v_cos_f32_e32 v224, v220
	v_cos_f32_e32 v225, v221
	v_cos_f32_e32 v226, v222
	v_cos_f32_e32 v227, v223
	v_sin_f32_e32 v220, v220
	v_sin_f32_e32 v221, v221
	v_sin_f32_e32 v222, v222
	v_sin_f32_e32 v223, v223
	s_waitcnt lgkmcnt(0)
	v_pk_mul_f32 v[216:217], v[216:217], v[220:221]
	v_pk_mul_f32 v[218:219], v[218:219], v[222:223]
	v_pk_fma_f32 v[60:61], v[60:61], v[224:225], v[216:217]
	v_pk_fma_f32 v[62:63], v[62:63], v[226:227], v[218:219]
	ds_bpermute_b32 v216, v213, v56
	ds_bpermute_b32 v217, v213, v57
	ds_bpermute_b32 v218, v213, v58
	ds_bpermute_b32 v219, v213, v59
	v_mul_f32_e32 v220, 0x3ad09b8a, v199
	v_mul_f32_e32 v221, 0x3a03ef5d, v199
	v_mul_f32_e32 v222, 0x3926e2d4, v199
	v_mul_f32_e32 v223, 0x38531894, v199
	v_cos_f32_e32 v224, v220
	v_cos_f32_e32 v225, v221
	v_cos_f32_e32 v226, v222
	v_cos_f32_e32 v227, v223
	v_sin_f32_e32 v220, v220
	v_sin_f32_e32 v221, v221
	v_sin_f32_e32 v222, v222
	v_sin_f32_e32 v223, v223
	s_waitcnt lgkmcnt(0)
	v_pk_mul_f32 v[216:217], v[216:217], v[220:221]
	v_pk_mul_f32 v[218:219], v[218:219], v[222:223]
	v_pk_fma_f32 v[56:57], v[56:57], v[224:225], v[216:217]
	v_pk_fma_f32 v[58:59], v[58:59], v[226:227], v[218:219]
	v_cvt_pk_bf16_f32 v60, v60, v61
	v_cvt_pk_bf16_f32 v61, v62, v63
	v_cvt_pk_bf16_f32 v62, v56, v57
	v_cvt_pk_bf16_f32 v63, v58, v59
	global_store_dwordx4 v197, v[60:63], s[16:17]
	v_pk_mul_f32 v[52:53], v[52:53], v[196:197] op_sel_hi:[1,0]
	v_pk_mul_f32 v[54:55], v[54:55], v[196:197] op_sel_hi:[1,0]
	v_pk_mul_f32 v[48:49], v[48:49], v[196:197] op_sel_hi:[1,0]
	v_pk_mul_f32 v[50:51], v[50:51], v[196:197] op_sel_hi:[1,0]
	v_cvt_pk_bf16_f32 v52, v52, v53
	v_cvt_pk_bf16_f32 v53, v54, v55
	v_cvt_pk_bf16_f32 v54, v48, v49
	v_cvt_pk_bf16_f32 v55, v50, v51
	global_store_dwordx4 v197, v[52:55], s[16:17] offset:256
	v_add_u32_e32 v197, 0x36000, v211
	v_pk_mul_f32 v[44:45], v[44:45], v[198:199] op_sel_hi:[1,0]
	v_pk_mul_f32 v[46:47], v[46:47], v[198:199] op_sel_hi:[1,0]
	v_pk_mul_f32 v[40:41], v[40:41], v[198:199] op_sel_hi:[1,0]
	v_pk_mul_f32 v[42:43], v[42:43], v[198:199] op_sel_hi:[1,0]
	v_mov_b32_e32 v199, s55
	v_cndmask_b32_e64 v199, v202, v199, s[10:11]
	v_cvt_f32_ubyte0_e32 v199, v199
	v_mul_f32_e32 v199, v174, v199
	ds_bpermute_b32 v216, v213, v44
	ds_bpermute_b32 v217, v213, v45
	ds_bpermute_b32 v218, v213, v46
	ds_bpermute_b32 v219, v213, v47
	v_mul_f32_e32 v220, 0x3e22f983, v199
	v_mul_f32_e32 v221, 0x3d4e2601, v199
	v_mul_f32_e32 v222, 0x3c826136, v199
	v_mul_f32_e32 v223, 0x3ba4eb34, v199
	v_cos_f32_e32 v224, v220
	v_cos_f32_e32 v225, v221
	v_cos_f32_e32 v226, v222
	v_cos_f32_e32 v227, v223
	v_sin_f32_e32 v220, v220
	v_sin_f32_e32 v221, v221
	v_sin_f32_e32 v222, v222
	v_sin_f32_e32 v223, v223
	s_waitcnt lgkmcnt(0)
	v_pk_mul_f32 v[216:217], v[216:217], v[220:221]
	v_pk_mul_f32 v[218:219], v[218:219], v[222:223]
	v_pk_fma_f32 v[44:45], v[44:45], v[224:225], v[216:217]
	v_pk_fma_f32 v[46:47], v[46:47], v[226:227], v[218:219]
	ds_bpermute_b32 v216, v213, v40
	ds_bpermute_b32 v217, v213, v41
	ds_bpermute_b32 v218, v213, v42
	ds_bpermute_b32 v219, v213, v43
	v_mul_f32_e32 v220, 0x3ad09b8a, v199
	v_mul_f32_e32 v221, 0x3a03ef5d, v199
	v_mul_f32_e32 v222, 0x3926e2d4, v199
	v_mul_f32_e32 v223, 0x38531894, v199
	v_cos_f32_e32 v224, v220
	v_cos_f32_e32 v225, v221
	v_cos_f32_e32 v226, v222
	v_cos_f32_e32 v227, v223
	v_sin_f32_e32 v220, v220
	v_sin_f32_e32 v221, v221
	v_sin_f32_e32 v222, v222
	v_sin_f32_e32 v223, v223
	s_waitcnt lgkmcnt(0)
	v_pk_mul_f32 v[216:217], v[216:217], v[220:221]
	v_pk_mul_f32 v[218:219], v[218:219], v[222:223]
	v_pk_fma_f32 v[40:41], v[40:41], v[224:225], v[216:217]
	v_pk_fma_f32 v[42:43], v[42:43], v[226:227], v[218:219]
	v_cvt_pk_bf16_f32 v44, v44, v45
	v_cvt_pk_bf16_f32 v45, v46, v47
	v_cvt_pk_bf16_f32 v46, v40, v41
	v_cvt_pk_bf16_f32 v47, v42, v43
	global_store_dwordx4 v197, v[44:47], s[16:17]
	v_pk_mul_f32 v[36:37], v[36:37], v[198:199] op_sel_hi:[1,0]
	v_pk_mul_f32 v[38:39], v[38:39], v[198:199] op_sel_hi:[1,0]
	v_pk_mul_f32 v[32:33], v[32:33], v[198:199] op_sel_hi:[1,0]
	v_pk_mul_f32 v[34:35], v[34:35], v[198:199] op_sel_hi:[1,0]
	v_cvt_pk_bf16_f32 v36, v36, v37
	v_cvt_pk_bf16_f32 v37, v38, v39
	v_cvt_pk_bf16_f32 v38, v32, v33
	v_cvt_pk_bf16_f32 v39, v34, v35
	global_store_dwordx4 v197, v[36:39], s[16:17] offset:256
	v_add_u32_e32 v197, 0x3c000, v211
	v_pk_mul_f32 v[28:29], v[28:29], v[210:211] op_sel_hi:[1,0]
	v_pk_mul_f32 v[30:31], v[30:31], v[210:211] op_sel_hi:[1,0]
	v_pk_mul_f32 v[24:25], v[24:25], v[210:211] op_sel_hi:[1,0]
	v_pk_mul_f32 v[26:27], v[26:27], v[210:211] op_sel_hi:[1,0]
	v_mov_b32_e32 v199, s55
	v_cndmask_b32_e64 v199, v203, v199, s[10:11]
	v_cvt_f32_ubyte0_e32 v199, v199
	v_mul_f32_e32 v199, v174, v199
	ds_bpermute_b32 v216, v213, v28
	ds_bpermute_b32 v217, v213, v29
	ds_bpermute_b32 v218, v213, v30
	ds_bpermute_b32 v219, v213, v31
	v_mul_f32_e32 v220, 0x3e22f983, v199
	v_mul_f32_e32 v221, 0x3d4e2601, v199
	v_mul_f32_e32 v222, 0x3c826136, v199
	v_mul_f32_e32 v223, 0x3ba4eb34, v199
	v_cos_f32_e32 v224, v220
	v_cos_f32_e32 v225, v221
	v_cos_f32_e32 v226, v222
	v_cos_f32_e32 v227, v223
	v_sin_f32_e32 v220, v220
	v_sin_f32_e32 v221, v221
	v_sin_f32_e32 v222, v222
	v_sin_f32_e32 v223, v223
	s_waitcnt lgkmcnt(0)
	v_pk_mul_f32 v[216:217], v[216:217], v[220:221]
	v_pk_mul_f32 v[218:219], v[218:219], v[222:223]
	v_pk_fma_f32 v[28:29], v[28:29], v[224:225], v[216:217]
	v_pk_fma_f32 v[30:31], v[30:31], v[226:227], v[218:219]
	ds_bpermute_b32 v216, v213, v24
	ds_bpermute_b32 v217, v213, v25
	ds_bpermute_b32 v218, v213, v26
	ds_bpermute_b32 v219, v213, v27
	v_mul_f32_e32 v220, 0x3ad09b8a, v199
	v_mul_f32_e32 v221, 0x3a03ef5d, v199
	v_mul_f32_e32 v222, 0x3926e2d4, v199
	v_mul_f32_e32 v223, 0x38531894, v199
	v_cos_f32_e32 v224, v220
	v_cos_f32_e32 v225, v221
	v_cos_f32_e32 v226, v222
	v_cos_f32_e32 v227, v223
	v_sin_f32_e32 v220, v220
	v_sin_f32_e32 v221, v221
	v_sin_f32_e32 v222, v222
	v_sin_f32_e32 v223, v223
	s_waitcnt lgkmcnt(0)
	v_pk_mul_f32 v[216:217], v[216:217], v[220:221]
	v_pk_mul_f32 v[218:219], v[218:219], v[222:223]
	v_pk_fma_f32 v[24:25], v[24:25], v[224:225], v[216:217]
	v_pk_fma_f32 v[26:27], v[26:27], v[226:227], v[218:219]
	v_cvt_pk_bf16_f32 v28, v28, v29
	v_cvt_pk_bf16_f32 v29, v30, v31
	v_cvt_pk_bf16_f32 v30, v24, v25
	v_cvt_pk_bf16_f32 v31, v26, v27
	global_store_dwordx4 v197, v[28:31], s[16:17]
	v_pk_mul_f32 v[20:21], v[20:21], v[210:211] op_sel_hi:[1,0]
	v_pk_mul_f32 v[22:23], v[22:23], v[210:211] op_sel_hi:[1,0]
	v_pk_mul_f32 v[16:17], v[16:17], v[210:211] op_sel_hi:[1,0]
	v_pk_mul_f32 v[18:19], v[18:19], v[210:211] op_sel_hi:[1,0]
	v_cvt_pk_bf16_f32 v20, v20, v21
	v_cvt_pk_bf16_f32 v21, v22, v23
	v_cvt_pk_bf16_f32 v22, v16, v17
	v_cvt_pk_bf16_f32 v23, v18, v19
	global_store_dwordx4 v197, v[20:23], s[16:17] offset:256
	v_add_u32_e32 v197, 0x42000, v211
	v_pk_mul_f32 v[12:13], v[12:13], v[212:213] op_sel_hi:[1,0]
	v_pk_mul_f32 v[14:15], v[14:15], v[212:213] op_sel_hi:[1,0]
	v_pk_mul_f32 v[8:9], v[8:9], v[212:213] op_sel_hi:[1,0]
	v_pk_mul_f32 v[10:11], v[10:11], v[212:213] op_sel_hi:[1,0]
	v_mov_b32_e32 v199, s55
	v_cndmask_b32_e64 v199, v204, v199, s[10:11]
	v_cvt_f32_ubyte0_e32 v199, v199
	v_mul_f32_e32 v199, v174, v199
	ds_bpermute_b32 v216, v213, v12
	ds_bpermute_b32 v217, v213, v13
	ds_bpermute_b32 v218, v213, v14
	ds_bpermute_b32 v219, v213, v15
	v_mul_f32_e32 v220, 0x3e22f983, v199
	v_mul_f32_e32 v221, 0x3d4e2601, v199
	v_mul_f32_e32 v222, 0x3c826136, v199
	v_mul_f32_e32 v223, 0x3ba4eb34, v199
	v_cos_f32_e32 v224, v220
	v_cos_f32_e32 v225, v221
	v_cos_f32_e32 v226, v222
	v_cos_f32_e32 v227, v223
	v_sin_f32_e32 v220, v220
	v_sin_f32_e32 v221, v221
	v_sin_f32_e32 v222, v222
	v_sin_f32_e32 v223, v223
	s_waitcnt lgkmcnt(0)
	v_pk_mul_f32 v[216:217], v[216:217], v[220:221]
	v_pk_mul_f32 v[218:219], v[218:219], v[222:223]
	v_pk_fma_f32 v[12:13], v[12:13], v[224:225], v[216:217]
	v_pk_fma_f32 v[14:15], v[14:15], v[226:227], v[218:219]
	ds_bpermute_b32 v216, v213, v8
	ds_bpermute_b32 v217, v213, v9
	ds_bpermute_b32 v218, v213, v10
	ds_bpermute_b32 v219, v213, v11
	v_mul_f32_e32 v220, 0x3ad09b8a, v199
	v_mul_f32_e32 v221, 0x3a03ef5d, v199
	v_mul_f32_e32 v222, 0x3926e2d4, v199
	v_mul_f32_e32 v223, 0x38531894, v199
	v_cos_f32_e32 v224, v220
	v_cos_f32_e32 v225, v221
	v_cos_f32_e32 v226, v222
	v_cos_f32_e32 v227, v223
	v_sin_f32_e32 v220, v220
	v_sin_f32_e32 v221, v221
	v_sin_f32_e32 v222, v222
	v_sin_f32_e32 v223, v223
	s_waitcnt lgkmcnt(0)
	v_pk_mul_f32 v[216:217], v[216:217], v[220:221]
	v_pk_mul_f32 v[218:219], v[218:219], v[222:223]
	v_pk_fma_f32 v[8:9], v[8:9], v[224:225], v[216:217]
	v_pk_fma_f32 v[10:11], v[10:11], v[226:227], v[218:219]
	v_cvt_pk_bf16_f32 v12, v12, v13
	v_cvt_pk_bf16_f32 v13, v14, v15
	v_cvt_pk_bf16_f32 v14, v8, v9
	v_cvt_pk_bf16_f32 v15, v10, v11
	global_store_dwordx4 v197, v[12:15], s[16:17]
	v_pk_mul_f32 v[4:5], v[4:5], v[212:213] op_sel_hi:[1,0]
	v_pk_mul_f32 v[6:7], v[6:7], v[212:213] op_sel_hi:[1,0]
	v_pk_mul_f32 v[0:1], v[0:1], v[212:213] op_sel_hi:[1,0]
	v_pk_mul_f32 v[2:3], v[2:3], v[212:213] op_sel_hi:[1,0]
	v_cvt_pk_bf16_f32 v4, v4, v5
	v_cvt_pk_bf16_f32 v5, v6, v7
	v_cvt_pk_bf16_f32 v6, v0, v1
	v_cvt_pk_bf16_f32 v7, v2, v3
	global_store_dwordx4 v197, v[4:7], s[16:17] offset:256
	s_branch .Lq2_end
.Lq2_v1:
	v_pk_mul_f32 v[148:149], v[148:149], v[196:197] op_sel_hi:[1,0]
	v_pk_mul_f32 v[150:151], v[150:151], v[196:197] op_sel_hi:[1,0]
	v_pk_mul_f32 v[144:145], v[144:145], v[196:197] op_sel_hi:[1,0]
	v_pk_mul_f32 v[146:147], v[146:147], v[196:197] op_sel_hi:[1,0]
	v_cvt_pk_bf16_f32 v148, v148, v149
	v_cvt_pk_bf16_f32 v149, v150, v151
	v_cvt_pk_bf16_f32 v150, v144, v145
	v_cvt_pk_bf16_f32 v151, v146, v147
	global_store_dwordx4 v211, v[148:151], s[16:17]
	v_pk_mul_f32 v[128:129], v[128:129], v[196:197] op_sel_hi:[1,0]
	v_pk_mul_f32 v[130:131], v[130:131], v[196:197] op_sel_hi:[1,0]
	v_pk_mul_f32 v[124:125], v[124:125], v[196:197] op_sel_hi:[1,0]
	v_pk_mul_f32 v[126:127], v[126:127], v[196:197] op_sel_hi:[1,0]
	v_mov_b32_e32 v199, s55
	v_cndmask_b32_e64 v199, v200, v199, s[10:11]
	v_cvt_f32_ubyte0_e32 v199, v199
	v_mul_f32_e32 v199, v174, v199
	ds_bpermute_b32 v216, v213, v128
	ds_bpermute_b32 v217, v213, v129
	ds_bpermute_b32 v218, v213, v130
	ds_bpermute_b32 v219, v213, v131
	v_mul_f32_e32 v220, 0x3e22f983, v199
	v_mul_f32_e32 v221, 0x3d4e2601, v199
	v_mul_f32_e32 v222, 0x3c826136, v199
	v_mul_f32_e32 v223, 0x3ba4eb34, v199
	v_cos_f32_e32 v224, v220
	v_cos_f32_e32 v225, v221
	v_cos_f32_e32 v226, v222
	v_cos_f32_e32 v227, v223
	v_sin_f32_e32 v220, v220
	v_sin_f32_e32 v221, v221
	v_sin_f32_e32 v222, v222
	v_sin_f32_e32 v223, v223
	s_waitcnt lgkmcnt(0)
	v_pk_mul_f32 v[216:217], v[216:217], v[220:221]
	v_pk_mul_f32 v[218:219], v[218:219], v[222:223]
	v_pk_fma_f32 v[128:129], v[128:129], v[224:225], v[216:217]
	v_pk_fma_f32 v[130:131], v[130:131], v[226:227], v[218:219]
	ds_bpermute_b32 v216, v213, v124
	ds_bpermute_b32 v217, v213, v125
	ds_bpermute_b32 v218, v213, v126
	ds_bpermute_b32 v219, v213, v127
	v_mul_f32_e32 v220, 0x3ad09b8a, v199
	v_mul_f32_e32 v221, 0x3a03ef5d, v199
	v_mul_f32_e32 v222, 0x3926e2d4, v199
	v_mul_f32_e32 v223, 0x38531894, v199
	v_cos_f32_e32 v224, v220
	v_cos_f32_e32 v225, v221
	v_cos_f32_e32 v226, v222
	v_cos_f32_e32 v227, v223
	v_sin_f32_e32 v220, v220
	v_sin_f32_e32 v221, v221
	v_sin_f32_e32 v222, v222
	v_sin_f32_e32 v223, v223
	s_waitcnt lgkmcnt(0)
	v_pk_mul_f32 v[216:217], v[216:217], v[220:221]
	v_pk_mul_f32 v[218:219], v[218:219], v[222:223]
	v_pk_fma_f32 v[124:125], v[124:125], v[224:225], v[216:217]
	v_pk_fma_f32 v[126:127], v[126:127], v[226:227], v[218:219]
	v_cvt_pk_bf16_f32 v128, v128, v129
	v_cvt_pk_bf16_f32 v129, v130, v131
	v_cvt_pk_bf16_f32 v130, v124, v125
	v_cvt_pk_bf16_f32 v131, v126, v127
	global_store_dwordx4 v211, v[128:131], s[16:17] offset:256
	v_add_u32_e32 v197, 0x6000, v211
	v_pk_mul_f32 v[108:109], v[108:109], v[198:199] op_sel_hi:[1,0]
	v_pk_mul_f32 v[110:111], v[110:111], v[198:199] op_sel_hi:[1,0]
	v_pk_mul_f32 v[104:105], v[104:105], v[198:199] op_sel_hi:[1,0]
	v_pk_mul_f32 v[106:107], v[106:107], v[198:199] op_sel_hi:[1,0]
	v_cvt_pk_bf16_f32 v108, v108, v109
	v_cvt_pk_bf16_f32 v109, v110, v111
	v_cvt_pk_bf16_f32 v110, v104, v105
	v_cvt_pk_bf16_f32 v111, v106, v107
	global_store_dwordx4 v197, v[108:111], s[16:17]
	v_pk_mul_f32 v[100:101], v[100:101], v[198:199] op_sel_hi:[1,0]
	v_pk_mul_f32 v[102:103], v[102:103], v[198:199] op_sel_hi:[1,0]
	v_pk_mul_f32 v[96:97], v[96:97], v[198:199] op_sel_hi:[1,0]
	v_pk_mul_f32 v[98:99], v[98:99], v[198:199] op_sel_hi:[1,0]
	v_mov_b32_e32 v199, s55
	v_cndmask_b32_e64 v199, v202, v199, s[10:11]
	v_cvt_f32_ubyte0_e32 v199, v199
	v_mul_f32_e32 v199, v174, v199
	ds_bpermute_b32 v216, v213, v100
	ds_bpermute_b32 v217, v213, v101
	ds_bpermute_b32 v218, v213, v102
	ds_bpermute_b32 v219, v213, v103
	v_mul_f32_e32 v220, 0x3e22f983, v199
	v_mul_f32_e32 v221, 0x3d4e2601, v199
	v_mul_f32_e32 v222, 0x3c826136, v199
	v_mul_f32_e32 v223, 0x3ba4eb34, v199
	v_cos_f32_e32 v224, v220
	v_cos_f32_e32 v225, v221
	v_cos_f32_e32 v226, v222
	v_cos_f32_e32 v227, v223
	v_sin_f32_e32 v220, v220
	v_sin_f32_e32 v221, v221
	v_sin_f32_e32 v222, v222
	v_sin_f32_e32 v223, v223
	s_waitcnt lgkmcnt(0)
	v_pk_mul_f32 v[216:217], v[216:217], v[220:221]
	v_pk_mul_f32 v[218:219], v[218:219], v[222:223]
	v_pk_fma_f32 v[100:101], v[100:101], v[224:225], v[216:217]
	v_pk_fma_f32 v[102:103], v[102:103], v[226:227], v[218:219]
	ds_bpermute_b32 v216, v213, v96
	ds_bpermute_b32 v217, v213, v97
	ds_bpermute_b32 v218, v213, v98
	ds_bpermute_b32 v219, v213, v99
	v_mul_f32_e32 v220, 0x3ad09b8a, v199
	v_mul_f32_e32 v221, 0x3a03ef5d, v199
	v_mul_f32_e32 v222, 0x3926e2d4, v199
	v_mul_f32_e32 v223, 0x38531894, v199
	v_cos_f32_e32 v224, v220
	v_cos_f32_e32 v225, v221
	v_cos_f32_e32 v226, v222
	v_cos_f32_e32 v227, v223
	v_sin_f32_e32 v220, v220
	v_sin_f32_e32 v221, v221
	v_sin_f32_e32 v222, v222
	v_sin_f32_e32 v223, v223
	s_waitcnt lgkmcnt(0)
	v_pk_mul_f32 v[216:217], v[216:217], v[220:221]
	v_pk_mul_f32 v[218:219], v[218:219], v[222:223]
	v_pk_fma_f32 v[96:97], v[96:97], v[224:225], v[216:217]
	v_pk_fma_f32 v[98:99], v[98:99], v[226:227], v[218:219]
	v_cvt_pk_bf16_f32 v100, v100, v101
	v_cvt_pk_bf16_f32 v101, v102, v103
	v_cvt_pk_bf16_f32 v102, v96, v97
	v_cvt_pk_bf16_f32 v103, v98, v99
	global_store_dwordx4 v197, v[100:103], s[16:17] offset:256
	v_add_u32_e32 v197, 0xc000, v211
	v_pk_mul_f32 v[92:93], v[92:93], v[210:211] op_sel_hi:[1,0]
	v_pk_mul_f32 v[94:95], v[94:95], v[210:211] op_sel_hi:[1,0]
	v_pk_mul_f32 v[88:89], v[88:89], v[210:211] op_sel_hi:[1,0]
	v_pk_mul_f32 v[90:91], v[90:91], v[210:211] op_sel_hi:[1,0]
	v_cvt_pk_bf16_f32 v92, v92, v93
	v_cvt_pk_bf16_f32 v93, v94, v95
	v_cvt_pk_bf16_f32 v94, v88, v89
	v_cvt_pk_bf16_f32 v95, v90, v91
	global_store_dwordx4 v197, v[92:95], s[16:17]
	v_pk_mul_f32 v[84:85], v[84:85], v[210:211] op_sel_hi:[1,0]
	v_pk_mul_f32 v[86:87], v[86:87], v[210:211] op_sel_hi:[1,0]
	v_pk_mul_f32 v[80:81], v[80:81], v[210:211] op_sel_hi:[1,0]
	v_pk_mul_f32 v[82:83], v[82:83], v[210:211] op_sel_hi:[1,0]
	v_mov_b32_e32 v199, s55
	v_cndmask_b32_e64 v199, v203, v199, s[10:11]
	v_cvt_f32_ubyte0_e32 v199, v199
	v_mul_f32_e32 v199, v174, v199
	ds_bpermute_b32 v216, v213, v84
	ds_bpermute_b32 v217, v213, v85
	ds_bpermute_b32 v218, v213, v86
	ds_bpermute_b32 v219, v213, v87
	v_mul_f32_e32 v220, 0x3e22f983, v199
	v_mul_f32_e32 v221, 0x3d4e2601, v199
	v_mul_f32_e32 v222, 0x3c826136, v199
	v_mul_f32_e32 v223, 0x3ba4eb34, v199
	v_cos_f32_e32 v224, v220
	v_cos_f32_e32 v225, v221
	v_cos_f32_e32 v226, v222
	v_cos_f32_e32 v227, v223
	v_sin_f32_e32 v220, v220
	v_sin_f32_e32 v221, v221
	v_sin_f32_e32 v222, v222
	v_sin_f32_e32 v223, v223
	s_waitcnt lgkmcnt(0)
	v_pk_mul_f32 v[216:217], v[216:217], v[220:221]
	v_pk_mul_f32 v[218:219], v[218:219], v[222:223]
	v_pk_fma_f32 v[84:85], v[84:85], v[224:225], v[216:217]
	v_pk_fma_f32 v[86:87], v[86:87], v[226:227], v[218:219]
	ds_bpermute_b32 v216, v213, v80
	ds_bpermute_b32 v217, v213, v81
	ds_bpermute_b32 v218, v213, v82
	ds_bpermute_b32 v219, v213, v83
	v_mul_f32_e32 v220, 0x3ad09b8a, v199
	v_mul_f32_e32 v221, 0x3a03ef5d, v199
	v_mul_f32_e32 v222, 0x3926e2d4, v199
	v_mul_f32_e32 v223, 0x38531894, v199
	v_cos_f32_e32 v224, v220
	v_cos_f32_e32 v225, v221
	v_cos_f32_e32 v226, v222
	v_cos_f32_e32 v227, v223
	v_sin_f32_e32 v220, v220
	v_sin_f32_e32 v221, v221
	v_sin_f32_e32 v222, v222
	v_sin_f32_e32 v223, v223
	s_waitcnt lgkmcnt(0)
	v_pk_mul_f32 v[216:217], v[216:217], v[220:221]
	v_pk_mul_f32 v[218:219], v[218:219], v[222:223]
	v_pk_fma_f32 v[80:81], v[80:81], v[224:225], v[216:217]
	v_pk_fma_f32 v[82:83], v[82:83], v[226:227], v[218:219]
	v_cvt_pk_bf16_f32 v84, v84, v85
	v_cvt_pk_bf16_f32 v85, v86, v87
	v_cvt_pk_bf16_f32 v86, v80, v81
	v_cvt_pk_bf16_f32 v87, v82, v83
	global_store_dwordx4 v197, v[84:87], s[16:17] offset:256
	v_add_u32_e32 v197, 0x12000, v211
	v_pk_mul_f32 v[76:77], v[76:77], v[212:213] op_sel_hi:[1,0]
	v_pk_mul_f32 v[78:79], v[78:79], v[212:213] op_sel_hi:[1,0]
	v_pk_mul_f32 v[72:73], v[72:73], v[212:213] op_sel_hi:[1,0]
	v_pk_mul_f32 v[74:75], v[74:75], v[212:213] op_sel_hi:[1,0]
	v_cvt_pk_bf16_f32 v76, v76, v77
	v_cvt_pk_bf16_f32 v77, v78, v79
	v_cvt_pk_bf16_f32 v78, v72, v73
	v_cvt_pk_bf16_f32 v79, v74, v75
	global_store_dwordx4 v197, v[76:79], s[16:17]
	v_pk_mul_f32 v[68:69], v[68:69], v[212:213] op_sel_hi:[1,0]
	v_pk_mul_f32 v[70:71], v[70:71], v[212:213] op_sel_hi:[1,0]
	v_pk_mul_f32 v[64:65], v[64:65], v[212:213] op_sel_hi:[1,0]
	v_pk_mul_f32 v[66:67], v[66:67], v[212:213] op_sel_hi:[1,0]
	v_mov_b32_e32 v199, s55
	v_cndmask_b32_e64 v199, v204, v199, s[10:11]
	v_cvt_f32_ubyte0_e32 v199, v199
	v_mul_f32_e32 v199, v174, v199
	ds_bpermute_b32 v216, v213, v68
	ds_bpermute_b32 v217, v213, v69
	ds_bpermute_b32 v218, v213, v70
	ds_bpermute_b32 v219, v213, v71
	v_mul_f32_e32 v220, 0x3e22f983, v199
	v_mul_f32_e32 v221, 0x3d4e2601, v199
	v_mul_f32_e32 v222, 0x3c826136, v199
	v_mul_f32_e32 v223, 0x3ba4eb34, v199
	v_cos_f32_e32 v224, v220
	v_cos_f32_e32 v225, v221
	v_cos_f32_e32 v226, v222
	v_cos_f32_e32 v227, v223
	v_sin_f32_e32 v220, v220
	v_sin_f32_e32 v221, v221
	v_sin_f32_e32 v222, v222
	v_sin_f32_e32 v223, v223
	s_waitcnt lgkmcnt(0)
	v_pk_mul_f32 v[216:217], v[216:217], v[220:221]
	v_pk_mul_f32 v[218:219], v[218:219], v[222:223]
	v_pk_fma_f32 v[68:69], v[68:69], v[224:225], v[216:217]
	v_pk_fma_f32 v[70:71], v[70:71], v[226:227], v[218:219]
	ds_bpermute_b32 v216, v213, v64
	ds_bpermute_b32 v217, v213, v65
	ds_bpermute_b32 v218, v213, v66
	ds_bpermute_b32 v219, v213, v67
	v_mul_f32_e32 v220, 0x3ad09b8a, v199
	v_mul_f32_e32 v221, 0x3a03ef5d, v199
	v_mul_f32_e32 v222, 0x3926e2d4, v199
	v_mul_f32_e32 v223, 0x38531894, v199
	v_cos_f32_e32 v224, v220
	v_cos_f32_e32 v225, v221
	v_cos_f32_e32 v226, v222
	v_cos_f32_e32 v227, v223
	v_sin_f32_e32 v220, v220
	v_sin_f32_e32 v221, v221
	v_sin_f32_e32 v222, v222
	v_sin_f32_e32 v223, v223
	s_waitcnt lgkmcnt(0)
	v_pk_mul_f32 v[216:217], v[216:217], v[220:221]
	v_pk_mul_f32 v[218:219], v[218:219], v[222:223]
	v_pk_fma_f32 v[64:65], v[64:65], v[224:225], v[216:217]
	v_pk_fma_f32 v[66:67], v[66:67], v[226:227], v[218:219]
	v_cvt_pk_bf16_f32 v68, v68, v69
	v_cvt_pk_bf16_f32 v69, v70, v71
	v_cvt_pk_bf16_f32 v70, v64, v65
	v_cvt_pk_bf16_f32 v71, v66, v67
	global_store_dwordx4 v197, v[68:71], s[16:17] offset:256
	s_mov_b32 s55, s7
	s_waitcnt vmcnt(8)
	v_pk_add_f32 v[112:113], v[112:113], v[114:115]
	v_pk_add_f32 v[116:117], v[116:117], v[118:119]
	v_pk_add_f32 v[120:121], v[120:121], v[122:123]
	v_pk_add_f32 v[112:113], v[112:113], v[116:117]
	v_pk_add_f32 v[112:113], v[112:113], v[120:121]
	v_add_f32_e32 v112, v112, v113
	v_fmamk_f32 v112, v112, 0x3b2aaaab, v208
	v_pk_add_f32 v[132:133], v[132:133], v[134:135]
	v_pk_add_f32 v[136:137], v[136:137], v[138:139]
	v_pk_add_f32 v[140:141], v[140:141], v[142:143]
	v_pk_add_f32 v[132:133], v[132:133], v[136:137]
	v_pk_add_f32 v[132:133], v[132:133], v[140:141]
	v_add_f32_e32 v132, v132, v133
	v_fmamk_f32 v132, v132, 0x3b2aaaab, v208
	v_pk_add_f32 v[152:153], v[152:153], v[154:155]
	v_pk_add_f32 v[156:157], v[156:157], v[158:159]
	v_pk_add_f32 v[160:161], v[160:161], v[162:163]
	v_pk_add_f32 v[152:153], v[152:153], v[156:157]
	v_pk_add_f32 v[152:153], v[152:153], v[160:161]
	v_add_f32_e32 v152, v152, v153
	v_fmamk_f32 v152, v152, 0x3b2aaaab, v208
	v_pk_add_f32 v[184:185], v[184:185], v[186:187]
	v_pk_add_f32 v[188:189], v[188:189], v[190:191]
	v_pk_add_f32 v[192:193], v[192:193], v[194:195]
	v_pk_add_f32 v[184:185], v[184:185], v[188:189]
	v_pk_add_f32 v[184:185], v[184:185], v[192:193]
	v_add_f32_e32 v184, v184, v185
	v_fmamk_f32 v184, v184, 0x3b2aaaab, v208
	v_rsq_f32_e32 v196, v112
	v_rsq_f32_e32 v198, v132
	v_rsq_f32_e32 v210, v152
	v_rsq_f32_e32 v212, v184
	s_nop 0
	v_mul_f32_e32 v196, 0x3e16c740, v196
	v_mul_f32_e32 v198, 0x3e16c740, v198
	v_mul_f32_e32 v210, 0x3e16c740, v210
	v_mul_f32_e32 v212, 0x3e16c740, v212
	v_add_u32_e32 v197, 0x30000, v211
	v_pk_mul_f32 v[60:61], v[60:61], v[196:197] op_sel_hi:[1,0]
	v_pk_mul_f32 v[62:63], v[62:63], v[196:197] op_sel_hi:[1,0]
	v_pk_mul_f32 v[56:57], v[56:57], v[196:197] op_sel_hi:[1,0]
	v_pk_mul_f32 v[58:59], v[58:59], v[196:197] op_sel_hi:[1,0]
	v_cvt_pk_bf16_f32 v60, v60, v61
	v_cvt_pk_bf16_f32 v61, v62, v63
	v_cvt_pk_bf16_f32 v62, v56, v57
	v_cvt_pk_bf16_f32 v63, v58, v59
	global_store_dwordx4 v197, v[60:63], s[16:17]
	v_pk_mul_f32 v[52:53], v[52:53], v[196:197] op_sel_hi:[1,0]
	v_pk_mul_f32 v[54:55], v[54:55], v[196:197] op_sel_hi:[1,0]
	v_pk_mul_f32 v[48:49], v[48:49], v[196:197] op_sel_hi:[1,0]
	v_pk_mul_f32 v[50:51], v[50:51], v[196:197] op_sel_hi:[1,0]
	v_mov_b32_e32 v199, s55
	v_cndmask_b32_e64 v199, v200, v199, s[10:11]
	v_cvt_f32_ubyte0_e32 v199, v199
	v_mul_f32_e32 v199, v174, v199
	ds_bpermute_b32 v216, v213, v52
	ds_bpermute_b32 v217, v213, v53
	ds_bpermute_b32 v218, v213, v54
	ds_bpermute_b32 v219, v213, v55
	v_mul_f32_e32 v220, 0x3e22f983, v199
	v_mul_f32_e32 v221, 0x3d4e2601, v199
	v_mul_f32_e32 v222, 0x3c826136, v199
	v_mul_f32_e32 v223, 0x3ba4eb34, v199
	v_cos_f32_e32 v224, v220
	v_cos_f32_e32 v225, v221
	v_cos_f32_e32 v226, v222
	v_cos_f32_e32 v227, v223
	v_sin_f32_e32 v220, v220
	v_sin_f32_e32 v221, v221
	v_sin_f32_e32 v222, v222
	v_sin_f32_e32 v223, v223
	s_waitcnt lgkmcnt(0)
	v_pk_mul_f32 v[216:217], v[216:217], v[220:221]
	v_pk_mul_f32 v[218:219], v[218:219], v[222:223]
	v_pk_fma_f32 v[52:53], v[52:53], v[224:225], v[216:217]
	v_pk_fma_f32 v[54:55], v[54:55], v[226:227], v[218:219]
	ds_bpermute_b32 v216, v213, v48
	ds_bpermute_b32 v217, v213, v49
	ds_bpermute_b32 v218, v213, v50
	ds_bpermute_b32 v219, v213, v51
	v_mul_f32_e32 v220, 0x3ad09b8a, v199
	v_mul_f32_e32 v221, 0x3a03ef5d, v199
	v_mul_f32_e32 v222, 0x3926e2d4, v199
	v_mul_f32_e32 v223, 0x38531894, v199
	v_cos_f32_e32 v224, v220
	v_cos_f32_e32 v225, v221
	v_cos_f32_e32 v226, v222
	v_cos_f32_e32 v227, v223
	v_sin_f32_e32 v220, v220
	v_sin_f32_e32 v221, v221
	v_sin_f32_e32 v222, v222
	v_sin_f32_e32 v223, v223
	s_waitcnt lgkmcnt(0)
	v_pk_mul_f32 v[216:217], v[216:217], v[220:221]
	v_pk_mul_f32 v[218:219], v[218:219], v[222:223]
	v_pk_fma_f32 v[48:49], v[48:49], v[224:225], v[216:217]
	v_pk_fma_f32 v[50:51], v[50:51], v[226:227], v[218:219]
	v_cvt_pk_bf16_f32 v52, v52, v53
	v_cvt_pk_bf16_f32 v53, v54, v55
	v_cvt_pk_bf16_f32 v54, v48, v49
	v_cvt_pk_bf16_f32 v55, v50, v51
	global_store_dwordx4 v197, v[52:55], s[16:17] offset:256
	v_add_u32_e32 v197, 0x36000, v211
	v_pk_mul_f32 v[44:45], v[44:45], v[198:199] op_sel_hi:[1,0]
	v_pk_mul_f32 v[46:47], v[46:47], v[198:199] op_sel_hi:[1,0]
	v_pk_mul_f32 v[40:41], v[40:41], v[198:199] op_sel_hi:[1,0]
	v_pk_mul_f32 v[42:43], v[42:43], v[198:199] op_sel_hi:[1,0]
	v_cvt_pk_bf16_f32 v44, v44, v45
	v_cvt_pk_bf16_f32 v45, v46, v47
	v_cvt_pk_bf16_f32 v46, v40, v41
	v_cvt_pk_bf16_f32 v47, v42, v43
	global_store_dwordx4 v197, v[44:47], s[16:17]
	v_pk_mul_f32 v[36:37], v[36:37], v[198:199] op_sel_hi:[1,0]
	v_pk_mul_f32 v[38:39], v[38:39], v[198:199] op_sel_hi:[1,0]
	v_pk_mul_f32 v[32:33], v[32:33], v[198:199] op_sel_hi:[1,0]
	v_pk_mul_f32 v[34:35], v[34:35], v[198:199] op_sel_hi:[1,0]
	v_mov_b32_e32 v199, s55
	v_cndmask_b32_e64 v199, v202, v199, s[10:11]
	v_cvt_f32_ubyte0_e32 v199, v199
	v_mul_f32_e32 v199, v174, v199
	ds_bpermute_b32 v216, v213, v36
	ds_bpermute_b32 v217, v213, v37
	ds_bpermute_b32 v218, v213, v38
	ds_bpermute_b32 v219, v213, v39
	v_mul_f32_e32 v220, 0x3e22f983, v199
	v_mul_f32_e32 v221, 0x3d4e2601, v199
	v_mul_f32_e32 v222, 0x3c826136, v199
	v_mul_f32_e32 v223, 0x3ba4eb34, v199
	v_cos_f32_e32 v224, v220
	v_cos_f32_e32 v225, v221
	v_cos_f32_e32 v226, v222
	v_cos_f32_e32 v227, v223
	v_sin_f32_e32 v220, v220
	v_sin_f32_e32 v221, v221
	v_sin_f32_e32 v222, v222
	v_sin_f32_e32 v223, v223
	s_waitcnt lgkmcnt(0)
	v_pk_mul_f32 v[216:217], v[216:217], v[220:221]
	v_pk_mul_f32 v[218:219], v[218:219], v[222:223]
	v_pk_fma_f32 v[36:37], v[36:37], v[224:225], v[216:217]
	v_pk_fma_f32 v[38:39], v[38:39], v[226:227], v[218:219]
	ds_bpermute_b32 v216, v213, v32
	ds_bpermute_b32 v217, v213, v33
	ds_bpermute_b32 v218, v213, v34
	ds_bpermute_b32 v219, v213, v35
	v_mul_f32_e32 v220, 0x3ad09b8a, v199
	v_mul_f32_e32 v221, 0x3a03ef5d, v199
	v_mul_f32_e32 v222, 0x3926e2d4, v199
	v_mul_f32_e32 v223, 0x38531894, v199
	v_cos_f32_e32 v224, v220
	v_cos_f32_e32 v225, v221
	v_cos_f32_e32 v226, v222
	v_cos_f32_e32 v227, v223
	v_sin_f32_e32 v220, v220
	v_sin_f32_e32 v221, v221
	v_sin_f32_e32 v222, v222
	v_sin_f32_e32 v223, v223
	s_waitcnt lgkmcnt(0)
	v_pk_mul_f32 v[216:217], v[216:217], v[220:221]
	v_pk_mul_f32 v[218:219], v[218:219], v[222:223]
	v_pk_fma_f32 v[32:33], v[32:33], v[224:225], v[216:217]
	v_pk_fma_f32 v[34:35], v[34:35], v[226:227], v[218:219]
	v_cvt_pk_bf16_f32 v36, v36, v37
	v_cvt_pk_bf16_f32 v37, v38, v39
	v_cvt_pk_bf16_f32 v38, v32, v33
	v_cvt_pk_bf16_f32 v39, v34, v35
	global_store_dwordx4 v197, v[36:39], s[16:17] offset:256
	v_add_u32_e32 v197, 0x3c000, v211
	v_pk_mul_f32 v[28:29], v[28:29], v[210:211] op_sel_hi:[1,0]
	v_pk_mul_f32 v[30:31], v[30:31], v[210:211] op_sel_hi:[1,0]
	v_pk_mul_f32 v[24:25], v[24:25], v[210:211] op_sel_hi:[1,0]
	v_pk_mul_f32 v[26:27], v[26:27], v[210:211] op_sel_hi:[1,0]
	v_cvt_pk_bf16_f32 v28, v28, v29
	v_cvt_pk_bf16_f32 v29, v30, v31
	v_cvt_pk_bf16_f32 v30, v24, v25
	v_cvt_pk_bf16_f32 v31, v26, v27
	global_store_dwordx4 v197, v[28:31], s[16:17]
	v_pk_mul_f32 v[20:21], v[20:21], v[210:211] op_sel_hi:[1,0]
	v_pk_mul_f32 v[22:23], v[22:23], v[210:211] op_sel_hi:[1,0]
	v_pk_mul_f32 v[16:17], v[16:17], v[210:211] op_sel_hi:[1,0]
	v_pk_mul_f32 v[18:19], v[18:19], v[210:211] op_sel_hi:[1,0]
	v_mov_b32_e32 v199, s55
	v_cndmask_b32_e64 v199, v203, v199, s[10:11]
	v_cvt_f32_ubyte0_e32 v199, v199
	v_mul_f32_e32 v199, v174, v199
	ds_bpermute_b32 v216, v213, v20
	ds_bpermute_b32 v217, v213, v21
	ds_bpermute_b32 v218, v213, v22
	ds_bpermute_b32 v219, v213, v23
	v_mul_f32_e32 v220, 0x3e22f983, v199
	v_mul_f32_e32 v221, 0x3d4e2601, v199
	v_mul_f32_e32 v222, 0x3c826136, v199
	v_mul_f32_e32 v223, 0x3ba4eb34, v199
	v_cos_f32_e32 v224, v220
	v_cos_f32_e32 v225, v221
	v_cos_f32_e32 v226, v222
	v_cos_f32_e32 v227, v223
	v_sin_f32_e32 v220, v220
	v_sin_f32_e32 v221, v221
	v_sin_f32_e32 v222, v222
	v_sin_f32_e32 v223, v223
	s_waitcnt lgkmcnt(0)
	v_pk_mul_f32 v[216:217], v[216:217], v[220:221]
	v_pk_mul_f32 v[218:219], v[218:219], v[222:223]
	v_pk_fma_f32 v[20:21], v[20:21], v[224:225], v[216:217]
	v_pk_fma_f32 v[22:23], v[22:23], v[226:227], v[218:219]
	ds_bpermute_b32 v216, v213, v16
	ds_bpermute_b32 v217, v213, v17
	ds_bpermute_b32 v218, v213, v18
	ds_bpermute_b32 v219, v213, v19
	v_mul_f32_e32 v220, 0x3ad09b8a, v199
	v_mul_f32_e32 v221, 0x3a03ef5d, v199
	v_mul_f32_e32 v222, 0x3926e2d4, v199
	v_mul_f32_e32 v223, 0x38531894, v199
	v_cos_f32_e32 v224, v220
	v_cos_f32_e32 v225, v221
	v_cos_f32_e32 v226, v222
	v_cos_f32_e32 v227, v223
	v_sin_f32_e32 v220, v220
	v_sin_f32_e32 v221, v221
	v_sin_f32_e32 v222, v222
	v_sin_f32_e32 v223, v223
	s_waitcnt lgkmcnt(0)
	v_pk_mul_f32 v[216:217], v[216:217], v[220:221]
	v_pk_mul_f32 v[218:219], v[218:219], v[222:223]
	v_pk_fma_f32 v[16:17], v[16:17], v[224:225], v[216:217]
	v_pk_fma_f32 v[18:19], v[18:19], v[226:227], v[218:219]
	v_cvt_pk_bf16_f32 v20, v20, v21
	v_cvt_pk_bf16_f32 v21, v22, v23
	v_cvt_pk_bf16_f32 v22, v16, v17
	v_cvt_pk_bf16_f32 v23, v18, v19
	global_store_dwordx4 v197, v[20:23], s[16:17] offset:256
	v_add_u32_e32 v197, 0x42000, v211
	v_pk_mul_f32 v[12:13], v[12:13], v[212:213] op_sel_hi:[1,0]
	v_pk_mul_f32 v[14:15], v[14:15], v[212:213] op_sel_hi:[1,0]
	v_pk_mul_f32 v[8:9], v[8:9], v[212:213] op_sel_hi:[1,0]
	v_pk_mul_f32 v[10:11], v[10:11], v[212:213] op_sel_hi:[1,0]
	v_cvt_pk_bf16_f32 v12, v12, v13
	v_cvt_pk_bf16_f32 v13, v14, v15
	v_cvt_pk_bf16_f32 v14, v8, v9
	v_cvt_pk_bf16_f32 v15, v10, v11
	global_store_dwordx4 v197, v[12:15], s[16:17]
	v_pk_mul_f32 v[4:5], v[4:5], v[212:213] op_sel_hi:[1,0]
	v_pk_mul_f32 v[6:7], v[6:7], v[212:213] op_sel_hi:[1,0]
	v_pk_mul_f32 v[0:1], v[0:1], v[212:213] op_sel_hi:[1,0]
	v_pk_mul_f32 v[2:3], v[2:3], v[212:213] op_sel_hi:[1,0]
	v_mov_b32_e32 v199, s55
	v_cndmask_b32_e64 v199, v204, v199, s[10:11]
	v_cvt_f32_ubyte0_e32 v199, v199
	v_mul_f32_e32 v199, v174, v199
	ds_bpermute_b32 v216, v213, v4
	ds_bpermute_b32 v217, v213, v5
	ds_bpermute_b32 v218, v213, v6
	ds_bpermute_b32 v219, v213, v7
	v_mul_f32_e32 v220, 0x3e22f983, v199
	v_mul_f32_e32 v221, 0x3d4e2601, v199
	v_mul_f32_e32 v222, 0x3c826136, v199
	v_mul_f32_e32 v223, 0x3ba4eb34, v199
	v_cos_f32_e32 v224, v220
	v_cos_f32_e32 v225, v221
	v_cos_f32_e32 v226, v222
	v_cos_f32_e32 v227, v223
	v_sin_f32_e32 v220, v220
	v_sin_f32_e32 v221, v221
	v_sin_f32_e32 v222, v222
	v_sin_f32_e32 v223, v223
	s_waitcnt lgkmcnt(0)
	v_pk_mul_f32 v[216:217], v[216:217], v[220:221]
	v_pk_mul_f32 v[218:219], v[218:219], v[222:223]
	v_pk_fma_f32 v[4:5], v[4:5], v[224:225], v[216:217]
	v_pk_fma_f32 v[6:7], v[6:7], v[226:227], v[218:219]
	ds_bpermute_b32 v216, v213, v0
	ds_bpermute_b32 v217, v213, v1
	ds_bpermute_b32 v218, v213, v2
	ds_bpermute_b32 v219, v213, v3
	v_mul_f32_e32 v220, 0x3ad09b8a, v199
	v_mul_f32_e32 v221, 0x3a03ef5d, v199
	v_mul_f32_e32 v222, 0x3926e2d4, v199
	v_mul_f32_e32 v223, 0x38531894, v199
	v_cos_f32_e32 v224, v220
	v_cos_f32_e32 v225, v221
	v_cos_f32_e32 v226, v222
	v_cos_f32_e32 v227, v223
	v_sin_f32_e32 v220, v220
	v_sin_f32_e32 v221, v221
	v_sin_f32_e32 v222, v222
	v_sin_f32_e32 v223, v223
	s_waitcnt lgkmcnt(0)
	v_pk_mul_f32 v[216:217], v[216:217], v[220:221]
	v_pk_mul_f32 v[218:219], v[218:219], v[222:223]
	v_pk_fma_f32 v[0:1], v[0:1], v[224:225], v[216:217]
	v_pk_fma_f32 v[2:3], v[2:3], v[226:227], v[218:219]
	v_cvt_pk_bf16_f32 v4, v4, v5
	v_cvt_pk_bf16_f32 v5, v6, v7
	v_cvt_pk_bf16_f32 v6, v0, v1
	v_cvt_pk_bf16_f32 v7, v2, v3
	global_store_dwordx4 v197, v[4:7], s[16:17] offset:256
.Lq2_end:
	s_and_b64 vcc, exec, s[4:5]
	s_mov_b64 s[2:3], -1
	s_cbranch_vccnz .LBB0_826
	s_andn2_b64 vcc, exec, s[14:15]
	s_cbranch_vccnz .LBB0_825
	s_barrier
	s_branch .LBB0_825
